# P3 q8 Q-output loop software-pipelined: 8 LDS reads in flight with counted lgkmcnt instead of one LDS round trip per store
# speedup vs baseline: 1.0030x; 1.0030x over previous
.LBB0_229:
	v_add_co_u32_e32 v10, vcc, 0x1899b600, v2
	s_nop 1
	v_addc_co_u32_e32 v11, vcc, 0, v3, vcc
	v_add_u32_e32 v12, 0x10800, v4
	ds_read_b128 v[16:19], v4
	ds_read_b128 v[20:23], v4 offset:8448
	ds_read_b128 v[24:27], v4 offset:16896
	ds_read_b128 v[28:31], v4 offset:25344
	ds_read_b128 v[32:35], v4 offset:33792
	ds_read_b128 v[36:39], v4 offset:42240
	ds_read_b128 v[40:43], v4 offset:50688
	ds_read_b128 v[44:47], v4 offset:59136
	s_waitcnt lgkmcnt(7)
	global_store_dwordx4 v[10:11], v[16:19], off
	v_add_co_u32_e32 v10, vcc, 0x1800, v10
	s_nop 1
	v_addc_co_u32_e32 v11, vcc, 0, v11, vcc
	ds_read_b128 v[48:51], v12
	s_waitcnt lgkmcnt(7)
	global_store_dwordx4 v[10:11], v[20:23], off
	v_add_co_u32_e32 v10, vcc, 0x1800, v10
	s_nop 1
	v_addc_co_u32_e32 v11, vcc, 0, v11, vcc
	ds_read_b128 v[52:55], v12 offset:8448
	s_waitcnt lgkmcnt(7)
	global_store_dwordx4 v[10:11], v[24:27], off
	v_add_co_u32_e32 v10, vcc, 0x1800, v10
	s_nop 1
	v_addc_co_u32_e32 v11, vcc, 0, v11, vcc
	ds_read_b128 v[56:59], v12 offset:16896
	s_waitcnt lgkmcnt(7)
	global_store_dwordx4 v[10:11], v[28:31], off
	v_add_co_u32_e32 v10, vcc, 0x1800, v10
	s_nop 1
	v_addc_co_u32_e32 v11, vcc, 0, v11, vcc
	ds_read_b128 v[60:63], v12 offset:25344
	s_waitcnt lgkmcnt(7)
	global_store_dwordx4 v[10:11], v[32:35], off
	v_add_co_u32_e32 v10, vcc, 0x1800, v10
	s_nop 1
	v_addc_co_u32_e32 v11, vcc, 0, v11, vcc
	ds_read_b128 v[64:67], v12 offset:33792
	s_waitcnt lgkmcnt(7)
	global_store_dwordx4 v[10:11], v[36:39], off
	v_add_co_u32_e32 v10, vcc, 0x1800, v10
	s_nop 1
	v_addc_co_u32_e32 v11, vcc, 0, v11, vcc
	ds_read_b128 v[68:71], v12 offset:42240
	s_waitcnt lgkmcnt(7)
	global_store_dwordx4 v[10:11], v[40:43], off
	v_add_co_u32_e32 v10, vcc, 0x1800, v10
	s_nop 1
	v_addc_co_u32_e32 v11, vcc, 0, v11, vcc
	ds_read_b128 v[72:75], v12 offset:50688
	s_waitcnt lgkmcnt(7)
	global_store_dwordx4 v[10:11], v[44:47], off
	v_add_co_u32_e32 v10, vcc, 0x1800, v10
	s_nop 1
	v_addc_co_u32_e32 v11, vcc, 0, v11, vcc
	ds_read_b128 v[76:79], v12 offset:59136
	s_waitcnt lgkmcnt(7)
	global_store_dwordx4 v[10:11], v[48:51], off
	v_add_co_u32_e32 v10, vcc, 0x1800, v10
	s_nop 1
	v_addc_co_u32_e32 v11, vcc, 0, v11, vcc
	s_waitcnt lgkmcnt(6)
	global_store_dwordx4 v[10:11], v[52:55], off
	v_add_co_u32_e32 v10, vcc, 0x1800, v10
	s_nop 1
	v_addc_co_u32_e32 v11, vcc, 0, v11, vcc
	s_waitcnt lgkmcnt(5)
	global_store_dwordx4 v[10:11], v[56:59], off
	v_add_co_u32_e32 v10, vcc, 0x1800, v10
	s_nop 1
	v_addc_co_u32_e32 v11, vcc, 0, v11, vcc
	s_waitcnt lgkmcnt(4)
	global_store_dwordx4 v[10:11], v[60:63], off
	v_add_co_u32_e32 v10, vcc, 0x1800, v10
	s_nop 1
	v_addc_co_u32_e32 v11, vcc, 0, v11, vcc
	s_waitcnt lgkmcnt(3)
	global_store_dwordx4 v[10:11], v[64:67], off
	v_add_co_u32_e32 v10, vcc, 0x1800, v10
	s_nop 1
	v_addc_co_u32_e32 v11, vcc, 0, v11, vcc
	s_waitcnt lgkmcnt(2)
	global_store_dwordx4 v[10:11], v[68:71], off
	v_add_co_u32_e32 v10, vcc, 0x1800, v10
	s_nop 1
	v_addc_co_u32_e32 v11, vcc, 0, v11, vcc
	s_waitcnt lgkmcnt(1)
	global_store_dwordx4 v[10:11], v[72:75], off
	v_add_co_u32_e32 v10, vcc, 0x1800, v10
	s_nop 1
	v_addc_co_u32_e32 v11, vcc, 0, v11, vcc
	s_waitcnt lgkmcnt(0)
	global_store_dwordx4 v[10:11], v[76:79], off
	v_add_u32_e32 v4, 0x21000, v4
	s_mov_b64 s[20:21], 0x18000
	s_cmp_eq_u32 s20, 0x18000
	s_add_i32 s67, s67, 1
	s_add_u32 s88, s88, 0x30000
	s_addc_u32 s89, s89, 0
	s_cmp_eq_u32 s67, 3
	s_barrier
	s_cbranch_scc0 .LBB0_201
	s_movk_i32 s4, 0x100
	v_cmp_gt_i32_e32 vcc, s4, v192
	s_and_saveexec_b64 s[20:21], vcc
	s_cbranch_execz .LBB0_97
	v_lshl_add_u32 v2, v192, 4, 0
	v_add_u32_e32 v4, 0x21400, v2
	v_add_u32_e32 v2, s95, v192
	v_add_u32_e32 v0, 0x21000, v193
	v_ashrrev_i32_e32 v3, 31, v2
	ds_read_b32 v0, v0
	v_lshlrev_b64 v[2:3], 5, v[2:3]
	v_lshl_add_u64 v[2:3], s[0:1], 0, v[2:3]
	s_lshl_b32 s34, s66, 2
	v_lshl_add_u64 v[6:7], v[2:3], 0, s[34:35]
	ds_read_b128 v[2:5], v4
	s_waitcnt lgkmcnt(1)
	v_add_f32_e32 v0, 0x358637bd, v0
	v_mul_f32_e32 v0, 0x358637bd, v0
	s_mov_b32 s6, 0x3baaaaab
	s_mov_b32 s4, 0x45800000
	s_waitcnt lgkmcnt(0)
	v_pk_fma_f32 v[2:3], v[2:3], s[6:7], v[0:1] op_sel_hi:[1,0,0]
	v_pk_fma_f32 v[4:5], v[4:5], s[6:7], v[0:1] op_sel_hi:[1,0,0]
	v_mul_f32_e32 v8, 0x4b800000, v2
	v_cmp_gt_f32_e64 s[0:1], s61, v2
	v_cmp_gt_f32_e32 vcc, s61, v3
	v_mul_f32_e32 v0, 0x4b800000, v4
	v_cndmask_b32_e64 v2, v2, v8, s[0:1]
	v_mul_f32_e32 v8, 0x4b800000, v3
	v_cndmask_b32_e32 v3, v3, v8, vcc
	v_rsq_f32_e32 v2, v2
	v_rsq_f32_e32 v3, v3
	s_nop 0
	v_pk_mul_f32 v[8:9], v[2:3], s[4:5] op_sel_hi:[1,0]
	s_nop 0
	v_cndmask_b32_e64 v2, v2, v8, s[0:1]
	v_cmp_gt_f32_e64 s[0:1], s61, v4
	v_cndmask_b32_e32 v3, v3, v9, vcc
	v_cmp_gt_f32_e32 vcc, s61, v5
	v_cndmask_b32_e64 v0, v4, v0, s[0:1]
	v_rsq_f32_e32 v4, v0
	v_mul_f32_e32 v0, 0x4b800000, v5
	v_cndmask_b32_e32 v0, v5, v0, vcc
	v_rsq_f32_e32 v5, v0
	s_nop 0
	v_pk_mul_f32 v[8:9], v[4:5], s[4:5] op_sel_hi:[1,0]
	s_nop 0
	v_cndmask_b32_e32 v5, v5, v9, vcc
	v_add_co_u32_e32 v6, vcc, 0x205b000, v6
	v_cndmask_b32_e64 v4, v4, v8, s[0:1]
	s_nop 0
	v_addc_co_u32_e32 v7, vcc, 0, v7, vcc
	global_store_dwordx4 v[6:7], v[2:5], off offset:1536
	s_branch .LBB0_97
